# natten: groups 2-4 of the q/k gain loads issued together with group 1 (3 of 4 serial L2 round trips removed per unit)
# speedup vs baseline: 1.0245x; 1.0021x over previous
.LBB0_508:
	s_or_b64 exec, exec, s[58:59]
	s_waitcnt vmcnt(0)
	v_sub_u32_e64 v50, s80, 1 clamp
	v_and_b32_e32 v55, 0xffff0000, v31
	v_and_b32_e32 v59, 0xffff0000, v30
	v_and_b32_e32 v58, 0xffff0000, v32
	v_readfirstlane_b32 s58, v50
	v_lshlrev_b32_e32 v54, 16, v31
	v_mul_f32_e32 v50, v55, v55
	v_lshlrev_b32_e32 v57, 16, v30
	v_lshlrev_b32_e32 v56, 16, v32
	v_pk_mul_f32 v[30:31], v[58:59], v[58:59]
	v_pk_fma_f32 v[50:51], v[54:55], v[54:55], v[50:51] op_sel_hi:[1,1,0]
	v_pk_fma_f32 v[30:31], v[56:57], v[56:57], v[30:31]
	v_and_b32_e32 v53, 0xffff0000, v29
	v_pk_add_f32 v[50:51], v[30:31], v[50:51] op_sel:[1,0] op_sel_hi:[0,1]
	v_pk_add_f32 v[72:73], v[30:31], v[50:51]
	v_and_b32_e32 v51, 0xffff0000, v27
	v_and_b32_e32 v50, 0xffff0000, v26
	v_lshlrev_b32_e32 v31, 16, v27
	v_lshlrev_b32_e32 v30, 16, v26
	v_pk_mul_f32 v[26:27], v[50:51], v[50:51]
	v_and_b32_e32 v52, 0xffff0000, v28
	v_lshlrev_b32_e32 v60, 16, v33
	v_and_b32_e32 v61, 0xffff0000, v33
	v_pk_fma_f32 v[26:27], v[30:31], v[30:31], v[26:27]
	v_lshlrev_b32_e32 v33, 16, v29
	v_lshlrev_b32_e32 v32, 16, v28
	v_pk_mul_f32 v[28:29], v[52:53], v[52:53]
	v_pk_add_f32 v[26:27], v[26:27], v[26:27] op_sel:[0,1] op_sel_hi:[1,0]
	v_pk_fma_f32 v[74:75], v[32:33], v[32:33], v[28:29]
	v_lshlrev_b32_e32 v28, 16, v19
	v_pk_add_f32 v[76:77], v[74:75], v[26:27]
	v_and_b32_e32 v27, 0xffff0000, v18
	v_lshlrev_b32_e32 v26, 16, v18
	v_and_b32_e32 v29, 0xffff0000, v19
	v_lshlrev_b32_e32 v98, 16, v23
	v_lshlrev_b32_e32 v70, 16, v20
	v_and_b32_e32 v68, 0xffff0000, v20
	v_pk_mov_b32 v[18:19], v[20:21], v[24:25] op_sel:[1,0]
	v_mul_f32_e32 v20, v27, v27
	v_and_b32_e32 v97, 0xffff0000, v23
	v_mul_f32_e32 v23, v98, v98
	v_lshlrev_b32_e32 v71, 16, v22
	v_and_b32_e32 v69, 0xffff0000, v22
	v_lshlrev_b32_e32 v66, 16, v21
	v_pk_fma_f32 v[20:21], v[26:27], v[26:27], v[20:21] op_sel_hi:[1,1,0]
	v_mul_f32_e32 v22, v29, v29
	v_mul_f32_e32 v62, v97, v97
	v_mov_b32_e32 v21, v23
	v_pk_fma_f32 v[22:23], v[28:29], v[28:29], v[22:23] op_sel_hi:[1,1,0]
	v_and_b32_e32 v65, 0xffff0000, v19
	v_and_b32_e32 v64, 0xffff0000, v18
	v_pk_mul_f32 v[18:19], v[68:69], v[68:69]
	v_mov_b32_e32 v23, v62
	v_pk_fma_f32 v[18:19], v[70:71], v[70:71], v[18:19]
	v_pk_add_f32 v[20:21], v[20:21], v[22:23]
	v_lshlrev_b32_e32 v67, 16, v24
	v_pk_add_f32 v[18:19], v[18:19], v[20:21]
	v_pk_mul_f32 v[20:21], v[64:65], v[64:65]
	v_lshlrev_b32_e32 v63, 16, v25
	v_pk_fma_f32 v[20:21], v[66:67], v[66:67], v[20:21]
	v_mov_b32_e32 v22, v72
	v_pk_add_f32 v[18:19], v[20:21], v[18:19]
	v_mul_f32_e32 v20, v61, v61
	v_pk_fma_f32 v[20:21], v[60:61], v[60:61], v[20:21] op_sel_hi:[1,1,0]
	v_mov_b32_e32 v23, v63
	v_mov_b32_e32 v62, v20
	v_and_b32_e32 v96, 0xffff0000, v25
	v_pk_add_f32 v[20:21], v[20:21], v[72:73]
	v_pk_mul_f32 v[22:23], v[62:63], v[22:23]
	v_mul_f32_e32 v78, v96, v96
	v_mov_b32_e32 v21, v23
	v_pk_add_f32 v[22:23], v[74:75], v[76:77] op_sel:[1,0] op_sel_hi:[0,1]
	v_mov_b32_e32 v23, v78
	v_pk_add_f32 v[20:21], v[20:21], v[22:23]
	v_lshlrev_b32_e32 v108, 16, v39
	v_pk_add_f32 v[18:19], v[20:21], v[18:19]
	v_and_b32_e32 v109, 0xffff0000, v39
	v_add_f32_e32 v18, v18, v19
	ds_bpermute_b32 v19, v173, v18
	v_lshlrev_b32_e32 v39, 16, v41
	v_lshlrev_b32_e32 v99, 16, v38
	v_and_b32_e32 v101, 0xffff0000, v38
	v_mul_f32_e32 v106, v108, v108
	s_waitcnt lgkmcnt(0)
	v_add_f32_e32 v18, v18, v19
	ds_bpermute_b32 v19, v174, v18
	v_mul_f32_e32 v111, v109, v109
	v_and_b32_e32 v100, 0xffff0000, v36
	v_pk_mov_b32 v[102:103], v[36:37], v[40:41] op_sel:[1,0]
	v_and_b32_e32 v110, 0xffff0000, v41
	s_waitcnt lgkmcnt(0)
	v_add_f32_e32 v18, v18, v19
	v_fmamk_f32 v18, v18, 0x3c000000, v179
	v_cmp_gt_f32_e32 vcc, s60, v18
	v_mul_f32_e32 v19, 0x4b800000, v18
	v_lshlrev_b32_e32 v41, 16, v40
	v_cndmask_b32_e32 v18, v18, v19, vcc
	v_rsq_f32_e32 v18, v18
	v_lshlrev_b32_e32 v40, 16, v37
	v_and_b32_e32 v37, 0xffff0000, v103
	v_mul_f32_e32 v112, v110, v110
	v_mul_f32_e32 v19, 0x45800000, v18
	v_cndmask_b32_e32 v18, v18, v19, vcc
	v_mul_f32_e32 v62, 0x3db504f3, v18
	global_load_dwordx4 v[18:21], v[120:121], off offset:16
	global_load_dwordx4 v[22:25], v[120:121], off
	global_load_dwordx4 v[80:83], v[122:123], off offset:16
	global_load_dwordx4 v[72:75], v[122:123], off
	global_load_dwordx4 v[184:187], v[120:121], off offset:144
	global_load_dwordx4 v[188:191], v[120:121], off offset:128
	global_load_dwordx4 v[192:195], v[122:123], off offset:144
	global_load_dwordx4 v[196:199], v[122:123], off offset:128
	global_load_dwordx4 v[200:203], v[120:121], off offset:272
	global_load_dwordx4 v[204:207], v[120:121], off offset:256
	global_load_dwordx4 v[208:211], v[122:123], off offset:272
	global_load_dwordx4 v[212:215], v[122:123], off offset:256
	global_load_dwordx4 v[216:219], v[120:121], off offset:400
	global_load_dwordx4 v[220:223], v[120:121], off offset:384
	global_load_dwordx4 v[224:227], v[122:123], off offset:400
	global_load_dwordx4 v[238:241], v[122:123], off offset:384
	v_mul_f32_e32 v26, v62, v26
	v_mul_f32_e32 v27, v62, v27
	s_min_u32 s58, s58, 56
	s_sub_i32 s58, s58, s46
	v_mov_b32_e32 v145, 0
	s_cmp_lt_i32 s58, -11
	v_mov_b32_e32 v144, v145
	v_mov_b32_e32 v113, v145
	s_waitcnt vmcnt(12)
	v_pk_mul_f32 v[76:77], v[24:25], v[74:75]
	v_pk_mul_f32 v[78:79], v[22:23], v[72:73]
	v_pk_mul_f32 v[74:75], v[18:19], v[80:81]
	v_mul_f32_e32 v18, v62, v57
	v_mul_f32_e32 v19, v62, v59
	v_mul_f32_e32 v18, v78, v18
	v_mul_f32_e32 v19, v79, v19
	v_pk_mul_f32 v[72:73], v[20:21], v[82:83]
	v_cvt_pk_bf16_f32 v18, v18, v19
	v_mul_f32_e32 v19, v62, v54
	v_mul_f32_e32 v20, v62, v55
	v_mul_f32_e32 v19, v76, v19
	v_mul_f32_e32 v20, v77, v20
	v_cvt_pk_bf16_f32 v19, v19, v20
	v_mul_f32_e32 v20, v62, v56
	v_mul_f32_e32 v21, v62, v58
	v_mul_f32_e32 v20, v74, v20
	v_mul_f32_e32 v21, v75, v21
	v_cvt_pk_bf16_f32 v20, v20, v21
	v_mul_f32_e32 v21, v62, v60
	v_mul_f32_e32 v22, v62, v61
	v_mul_f32_e32 v21, v72, v21
	v_mul_f32_e32 v22, v73, v22
	v_cvt_pk_bf16_f32 v21, v21, v22
	s_waitcnt vmcnt(8)
	v_mov_b64_e32 v[22:23], v[184:185]
	v_mov_b64_e32 v[24:25], v[186:187]
	v_mov_b64_e32 v[54:55], v[188:189]
	v_mov_b64_e32 v[56:57], v[190:191]
	v_mov_b64_e32 v[58:59], v[192:193]
	v_mov_b64_e32 v[60:61], v[194:195]
	v_mov_b64_e32 v[80:81], v[196:197]
	v_mov_b64_e32 v[82:83], v[198:199]
	s_waitcnt vmcnt(8)
	v_pk_mul_f32 v[84:85], v[56:57], v[82:83]
	v_pk_mul_f32 v[86:87], v[54:55], v[80:81]
	v_pk_mul_f32 v[82:83], v[22:23], v[58:59]
	v_mul_f32_e32 v22, v62, v30
	v_mul_f32_e32 v23, v62, v50
	v_mul_f32_e32 v22, v22, v86
	v_mul_f32_e32 v23, v23, v87
	v_pk_mul_f32 v[80:81], v[24:25], v[60:61]
	v_cvt_pk_bf16_f32 v22, v22, v23
	v_mul_f32_e32 v23, v62, v31
	v_mul_f32_e32 v24, v62, v51
	v_mul_f32_e32 v23, v23, v84
	v_mul_f32_e32 v24, v24, v85
	v_cvt_pk_bf16_f32 v23, v23, v24
	v_mul_f32_e32 v24, v62, v32
	v_mul_f32_e32 v25, v62, v52
	v_mul_f32_e32 v24, v24, v82
	v_mul_f32_e32 v25, v25, v83
	v_cvt_pk_bf16_f32 v24, v24, v25
	v_mul_f32_e32 v25, v62, v33
	v_mul_f32_e32 v30, v62, v53
	v_mul_f32_e32 v25, v25, v80
	v_mul_f32_e32 v30, v30, v81
	v_cvt_pk_bf16_f32 v25, v25, v30
	s_waitcnt vmcnt(4)
	v_mov_b64_e32 v[30:31], v[200:201]
	v_mov_b64_e32 v[32:33], v[202:203]
	v_mov_b64_e32 v[50:51], v[204:205]
	v_mov_b64_e32 v[52:53], v[206:207]
	v_mov_b64_e32 v[54:55], v[208:209]
	v_mov_b64_e32 v[56:57], v[210:211]
	v_mov_b64_e32 v[58:59], v[212:213]
	v_mov_b64_e32 v[60:61], v[214:215]
	s_waitcnt vmcnt(4)
	v_pk_mul_f32 v[90:91], v[30:31], v[54:55]
	s_waitcnt vmcnt(4)
	v_pk_mul_f32 v[94:95], v[50:51], v[58:59]
	v_pk_mul_f32 v[92:93], v[52:53], v[60:61]
	v_mul_f32_e32 v26, v26, v94
	v_mul_f32_e32 v27, v27, v95
	v_cvt_pk_bf16_f32 v26, v26, v27
	v_mul_f32_e32 v27, v62, v28
	v_mul_f32_e32 v28, v62, v29
	v_mul_f32_e32 v27, v27, v92
	v_mul_f32_e32 v28, v28, v93
	v_cvt_pk_bf16_f32 v27, v27, v28
	v_mul_f32_e32 v28, v62, v70
	v_mul_f32_e32 v29, v62, v68
	v_mul_f32_e32 v28, v28, v90
	v_mul_f32_e32 v29, v29, v91
	v_pk_mul_f32 v[88:89], v[32:33], v[56:57]
	v_cvt_pk_bf16_f32 v28, v28, v29
	v_mul_f32_e32 v29, v62, v66
	v_mul_f32_e32 v30, v62, v64
	v_mul_f32_e32 v29, v29, v88
	v_mul_f32_e32 v30, v30, v89
	v_cvt_pk_bf16_f32 v29, v29, v30
	s_waitcnt vmcnt(0)
	v_mov_b64_e32 v[30:31], v[216:217]
	v_mov_b64_e32 v[32:33], v[218:219]
	v_mov_b64_e32 v[54:55], v[220:221]
	v_mov_b64_e32 v[56:57], v[222:223]
	v_mov_b64_e32 v[50:51], v[224:225]
	v_mov_b64_e32 v[52:53], v[226:227]
	v_mov_b64_e32 v[58:59], v[238:239]
	v_mov_b64_e32 v[60:61], v[240:241]
	v_lshlrev_b32_e32 v68, 16, v44
	v_and_b32_e32 v44, 0xffff0000, v44
	s_barrier
	s_waitcnt vmcnt(1)
	v_pk_mul_f32 v[50:51], v[30:31], v[50:51]
	s_waitcnt vmcnt(0)
	v_pk_mul_f32 v[58:59], v[54:55], v[58:59]
	v_mul_f32_e32 v30, v62, v71
	v_mul_f32_e32 v31, v62, v69
	v_mul_f32_e32 v30, v30, v58
	v_mul_f32_e32 v31, v31, v59
	v_pk_mul_f32 v[60:61], v[56:57], v[60:61]
	v_pk_mul_f32 v[52:53], v[32:33], v[52:53]
	v_cvt_pk_bf16_f32 v30, v30, v31
	v_mul_f32_e32 v31, v62, v98
	v_mul_f32_e32 v32, v62, v97
	v_mul_f32_e32 v31, v31, v60
	v_mul_f32_e32 v32, v32, v61
	v_cvt_pk_bf16_f32 v31, v31, v32
	v_mul_f32_e32 v32, v62, v67
	v_mul_f32_e32 v33, v62, v65
	v_mul_f32_e32 v32, v32, v50
	v_mul_f32_e32 v33, v33, v51
	v_cvt_pk_bf16_f32 v32, v32, v33
	v_mul_f32_e32 v33, v62, v63
	v_mul_f32_e32 v54, v62, v96
	v_and_b32_e32 v97, 0xffff0000, v34
	v_mul_f32_e32 v33, v33, v52
	v_mul_f32_e32 v54, v54, v53
	v_lshlrev_b32_e32 v56, 16, v47
	v_and_b32_e32 v57, 0xffff0000, v47
	v_lshlrev_b32_e32 v63, 16, v46
	v_and_b32_e32 v47, 0xffff0000, v46
	v_and_b32_e32 v46, 0xffff0000, v48
	v_lshlrev_b32_e32 v96, 16, v34
	v_lshlrev_b32_e32 v34, 16, v35
	v_and_b32_e32 v35, 0xffff0000, v35
	v_mul_f32_e32 v38, v97, v97
	v_cvt_pk_bf16_f32 v33, v33, v54
	v_mul_f32_e32 v54, v57, v57
	v_lshlrev_b32_e32 v62, 16, v48
	v_pk_mul_f32 v[64:65], v[46:47], v[46:47]
	v_pk_fma_f32 v[104:105], v[96:97], v[96:97], v[38:39] op_sel_hi:[1,1,0]
	v_mul_f32_e32 v38, v35, v35
	v_pk_fma_f32 v[54:55], v[56:57], v[56:57], v[54:55] op_sel_hi:[1,1,0]
	v_pk_fma_f32 v[64:65], v[62:63], v[62:63], v[64:65]
	v_mov_b32_e32 v105, v106
	v_pk_fma_f32 v[106:107], v[34:35], v[34:35], v[38:39] op_sel_hi:[1,1,0]
	v_pk_add_f32 v[54:55], v[64:65], v[54:55] op_sel:[1,0] op_sel_hi:[0,1]
	v_lshlrev_b32_e32 v98, 16, v36
	v_and_b32_e32 v36, 0xffff0000, v102
	v_pk_mul_f32 v[102:103], v[100:101], v[100:101]
	v_mov_b32_e32 v107, v111
	v_pk_add_f32 v[54:55], v[64:65], v[54:55]
	v_lshlrev_b32_e32 v65, 16, v43
	v_lshlrev_b32_e32 v64, 16, v42
	v_and_b32_e32 v43, 0xffff0000, v43
	v_and_b32_e32 v42, 0xffff0000, v42
	v_pk_fma_f32 v[102:103], v[98:99], v[98:99], v[102:103]
	v_pk_add_f32 v[104:105], v[104:105], v[106:107]
	v_lshlrev_b32_e32 v48, 16, v49
	v_and_b32_e32 v49, 0xffff0000, v49
	v_pk_mul_f32 v[66:67], v[42:43], v[42:43]
	v_lshlrev_b32_e32 v69, 16, v45
	v_and_b32_e32 v45, 0xffff0000, v45
	v_pk_add_f32 v[102:103], v[102:103], v[104:105]
	v_pk_mul_f32 v[104:105], v[36:37], v[36:37]
	v_pk_fma_f32 v[66:67], v[64:65], v[64:65], v[66:67]
	v_pk_mul_f32 v[70:71], v[44:45], v[44:45]
	v_pk_fma_f32 v[104:105], v[40:41], v[40:41], v[104:105]
	v_mul_f32_e32 v38, v49, v49
	v_pk_add_f32 v[66:67], v[66:67], v[66:67] op_sel:[0,1] op_sel_hi:[1,0]
	v_pk_fma_f32 v[70:71], v[68:69], v[68:69], v[70:71]
	v_pk_add_f32 v[102:103], v[104:105], v[102:103]
	v_pk_fma_f32 v[104:105], v[48:49], v[48:49], v[38:39] op_sel_hi:[1,1,0]
	v_pk_add_f32 v[66:67], v[70:71], v[66:67]
	v_mov_b32_e32 v38, v104
	v_mov_b32_e32 v106, v54
	v_mov_b32_e32 v107, v39
	v_pk_add_f32 v[54:55], v[104:105], v[54:55]
	v_pk_mul_f32 v[104:105], v[38:39], v[106:107]
	v_pk_add_f32 v[66:67], v[70:71], v[66:67] op_sel:[1,0] op_sel_hi:[0,1]
	v_mov_b32_e32 v55, v105
	v_mov_b32_e32 v67, v112
	v_pk_add_f32 v[54:55], v[54:55], v[66:67]
	v_mov_b32_e32 v105, v145
	v_pk_add_f32 v[54:55], v[54:55], v[102:103]
	v_mov_b32_e32 v104, v145
	v_add_f32_e32 v38, v54, v55
	ds_bpermute_b32 v54, v173, v38
	v_mov_b32_e32 v103, v145
	v_mov_b32_e32 v102, v145
	v_mov_b32_e32 v107, v145
	v_mov_b32_e32 v106, v145
	s_waitcnt lgkmcnt(0)
	v_add_f32_e32 v38, v38, v54
	ds_bpermute_b32 v54, v174, v38
	v_mov_b32_e32 v112, v145
	v_mov_b32_e32 v111, v145
	s_waitcnt lgkmcnt(0)
	v_add_f32_e32 v38, v38, v54
	v_fmamk_f32 v38, v38, 0x3c000000, v179
	v_cmp_gt_f32_e32 vcc, s60, v38
	v_mul_f32_e32 v54, 0x4b800000, v38
	s_nop 0
	v_cndmask_b32_e32 v38, v38, v54, vcc
	v_rsq_f32_e32 v38, v38
	s_nop 0
	v_mul_f32_e32 v54, 0x45800000, v38
	v_cndmask_b32_e32 v38, v38, v54, vcc
	v_mul_f32_e32 v38, 0x3db504f3, v38
	v_mul_f32_e32 v54, v38, v63
	v_mul_f32_e32 v47, v38, v47
	v_mul_f32_e32 v54, v78, v54
	v_mul_f32_e32 v47, v79, v47
	v_cvt_pk_bf16_f32 v54, v54, v47
	v_mul_f32_e32 v47, v38, v56
	v_mul_f32_e32 v55, v38, v57
	v_mul_f32_e32 v34, v38, v34
	v_mul_f32_e32 v47, v76, v47
	v_mul_f32_e32 v55, v77, v55
	v_mul_f32_e32 v46, v38, v46
	v_mul_f32_e32 v34, v92, v34
	v_mul_f32_e32 v35, v38, v35
	v_cvt_pk_bf16_f32 v55, v47, v55
	v_mul_f32_e32 v47, v38, v62
	v_mul_f32_e32 v46, v75, v46
	v_mul_f32_e32 v35, v93, v35
	v_cvt_pk_bf16_f32 v71, v34, v35
	v_mul_f32_e32 v34, v38, v98
	v_mul_f32_e32 v47, v74, v47
	v_cvt_pk_bf16_f32 v56, v47, v46
	v_mul_f32_e32 v46, v38, v48
	v_mul_f32_e32 v34, v90, v34
	v_mul_f32_e32 v35, v38, v100
	v_mul_f32_e32 v46, v72, v46
	v_mul_f32_e32 v35, v91, v35
	v_cvt_pk_bf16_f32 v72, v34, v35
	v_mul_f32_e32 v34, v38, v40
	v_mul_f32_e32 v47, v38, v49
	v_mul_f32_e32 v42, v38, v42
	v_mul_f32_e32 v34, v88, v34
	v_mul_f32_e32 v35, v38, v36
	v_mul_f32_e32 v47, v73, v47
	v_cvt_pk_bf16_f32 v57, v46, v47
	v_mul_f32_e32 v46, v38, v64
	v_mul_f32_e32 v42, v87, v42
	v_mul_f32_e32 v35, v89, v35
	v_cvt_pk_bf16_f32 v73, v34, v35
	v_mul_f32_e32 v34, v38, v99
	v_mul_f32_e32 v46, v86, v46
	v_cvt_pk_bf16_f32 v62, v46, v42
	v_mul_f32_e32 v42, v38, v65
	v_mul_f32_e32 v34, v58, v34
	v_mul_f32_e32 v35, v38, v101
	v_mul_f32_e32 v42, v84, v42
	v_mul_f32_e32 v43, v38, v43
	v_mul_f32_e32 v35, v59, v35
	v_cvt_pk_bf16_f32 v78, v34, v35
	v_mul_f32_e32 v34, v38, v108
	v_mul_f32_e32 v43, v85, v43
	v_cvt_pk_bf16_f32 v63, v42, v43
	v_mul_f32_e32 v42, v38, v68
	v_mul_f32_e32 v34, v60, v34
	v_mul_f32_e32 v35, v38, v109
	v_mul_f32_e32 v42, v82, v42
	v_mul_f32_e32 v43, v38, v44
	v_mul_f32_e32 v35, v61, v35
	v_cvt_pk_bf16_f32 v79, v34, v35
	v_mul_f32_e32 v34, v38, v41
	v_mul_f32_e32 v43, v83, v43
	v_cvt_pk_bf16_f32 v64, v42, v43
	v_mul_f32_e32 v42, v38, v69
	v_mul_f32_e32 v34, v50, v34
	v_mul_f32_e32 v35, v38, v37
	v_mul_f32_e32 v42, v80, v42
	v_mul_f32_e32 v43, v38, v45
	v_mul_f32_e32 v35, v51, v35
	v_cvt_pk_bf16_f32 v80, v34, v35
	v_mul_f32_e32 v34, v38, v39
	v_and_b32_e32 v47, 0xffff0000, v5
	v_and_b32_e32 v46, 0xffff0000, v4
	v_mul_f32_e32 v43, v81, v43
	v_cvt_pk_bf16_f32 v65, v42, v43
	v_mul_f32_e32 v42, v38, v96
	v_mul_f32_e32 v34, v52, v34
	v_mul_f32_e32 v35, v38, v110
	v_lshlrev_b32_e32 v45, 16, v5
	v_lshlrev_b32_e32 v44, 16, v4
	v_pk_mul_f32 v[48:49], v[46:47], v[46:47]
	v_mul_f32_e32 v42, v94, v42
	v_mul_f32_e32 v43, v38, v97
	v_mul_f32_e32 v35, v53, v35
	v_cvt_pk_bf16_f32 v81, v34, v35
	v_lshlrev_b32_e32 v34, 16, v2
	v_lshlrev_b32_e32 v38, 16, v3
	v_pk_fma_f32 v[48:49], v[44:45], v[44:45], v[48:49]
	v_mul_f32_e32 v43, v95, v43
	v_cvt_pk_bf16_f32 v70, v42, v43
	v_and_b32_e32 v35, 0xffff0000, v2
	v_mul_f32_e32 v36, v34, v34
	v_and_b32_e32 v39, 0xffff0000, v3
	v_mul_f32_e32 v42, v38, v38
	v_pk_add_f32 v[48:49], v[48:49], v[48:49] op_sel_hi:[0,1]
	v_lshlrev_b32_e32 v50, 16, v6
	v_lshlrev_b32_e32 v40, 16, v8
	v_pk_fma_f32 v[36:37], v[34:35], v[34:35], v[36:37] op_sel_hi:[1,1,0]
	v_pk_fma_f32 v[42:43], v[38:39], v[38:39], v[42:43] op_sel_hi:[1,1,0]
	v_and_b32_e32 v51, 0xffff0000, v6
	v_mul_f32_e32 v48, v50, v50
	v_lshlrev_b32_e32 v58, 16, v7
	v_pk_fma_f32 v[52:53], v[50:51], v[50:51], v[48:49] op_sel_hi:[1,1,0]
	v_and_b32_e32 v59, 0xffff0000, v7
	v_mul_f32_e32 v48, v58, v58
	v_mov_b32_e32 v41, v37
	v_mov_b32_e32 v66, v40
	v_mov_b32_e32 v67, v43
	v_and_b32_e32 v68, 0xffff0000, v8
	v_lshlrev_b32_e32 v69, 16, v9
	v_and_b32_e32 v74, 0xffff0000, v9
	v_pk_fma_f32 v[60:61], v[58:59], v[58:59], v[48:49] op_sel_hi:[1,1,0]
	v_pk_mul_f32 v[66:67], v[40:41], v[66:67]
	v_pk_add_f32 v[36:37], v[36:37], v[42:43]
	v_mul_f32_e32 v48, v68, v68
	v_mul_f32_e32 v52, v69, v69
	v_mul_f32_e32 v60, v74, v74
	v_mov_b32_e32 v67, v37
	v_pk_add_f32 v[36:37], v[66:67], v[48:49]
	v_pk_add_f32 v[42:43], v[52:53], v[60:61]
	v_mov_b32_e32 v49, v145
	v_pk_add_f32 v[36:37], v[36:37], v[42:43]
	v_mov_b32_e32 v43, v145
	v_add_f32_e32 v36, v36, v37
	ds_bpermute_b32 v37, v175, v36
	v_mov_b32_e32 v48, v145
	v_mov_b32_e32 v53, v145
	v_mov_b32_e32 v52, v145
	v_mov_b32_e32 v61, v145
	s_waitcnt lgkmcnt(0)
	v_add_f32_e32 v36, v36, v37
	ds_bpermute_b32 v37, v173, v36
	v_mov_b32_e32 v60, v145
	v_mov_b32_e32 v67, v145
	v_mov_b32_e32 v66, v145
	v_mov_b32_e32 v77, v145
	s_waitcnt lgkmcnt(0)
	v_add_f32_e32 v36, v36, v37
	ds_bpermute_b32 v37, v174, v36
	v_mov_b32_e32 v76, v145
	v_mov_b32_e32 v75, v145
	v_mov_b32_e32 v85, v145
	v_mov_b32_e32 v84, v145
	s_waitcnt lgkmcnt(0)
	v_add_f32_e32 v36, v36, v37
	v_fmamk_f32 v36, v36, 0x3c000000, v179
	v_cmp_gt_f32_e32 vcc, s60, v36
	v_mul_f32_e32 v37, 0x4b800000, v36
	v_mov_b32_e32 v83, v145
	v_cndmask_b32_e32 v36, v36, v37, vcc
	v_rsq_f32_e32 v36, v36
	v_mov_b32_e32 v82, v145
	v_mov_b32_e32 v89, v145
	v_mov_b32_e32 v88, v145
	v_mul_f32_e32 v37, 0x45800000, v36
	v_cndmask_b32_e32 v41, v36, v37, vcc
	v_mul_f32_e32 v34, v41, v34
	v_mul_f32_e32 v35, v41, v35
	v_cvt_pk_bf16_f32 v34, v34, v35
	v_mul_f32_e32 v35, v41, v38
	v_mul_f32_e32 v36, v41, v39
	v_cvt_pk_bf16_f32 v35, v35, v36
	v_mul_f32_e32 v36, v41, v44
	v_mul_f32_e32 v37, v41, v46
	v_cvt_pk_bf16_f32 v36, v36, v37
	v_mul_f32_e32 v37, v41, v45
	v_mul_f32_e32 v38, v41, v47
	v_cvt_pk_bf16_f32 v37, v37, v38
	v_mul_f32_e32 v38, v41, v50
	v_mul_f32_e32 v39, v41, v51
	v_cvt_pk_bf16_f32 v38, v38, v39
	v_mul_f32_e32 v39, v41, v58
	v_mul_f32_e32 v42, v41, v59
	v_cvt_pk_bf16_f32 v39, v39, v42
	v_mul_f32_e32 v40, v41, v40
	v_mul_f32_e32 v42, v41, v68
	v_cvt_pk_bf16_f32 v40, v40, v42
	v_mul_f32_e32 v42, v41, v69
	v_mul_f32_e32 v41, v41, v74
	v_cvt_pk_bf16_f32 v41, v42, v41
	v_add_u32_e32 v42, 0, v115
	ds_write_b128 v42, v[34:37]
	ds_write_b128 v42, v[38:41] offset:8192
	v_add_u32_e32 v34, 0, v127
	ds_write_b128 v34, v[10:13] offset:16384
	v_add_u32_e32 v34, 0, v129
	ds_write_b128 v34, v[14:17] offset:16384
	v_mov_b32_e32 v37, v145
	v_mov_b32_e32 v36, v145
	v_mov_b32_e32 v35, v145
	v_mov_b32_e32 v34, v145
	v_mov_b32_e32 v41, v145
	v_mov_b32_e32 v40, v145
	v_mov_b32_e32 v39, v145
	v_mov_b32_e32 v38, v145
	v_mov_b32_e32 v45, v145
	v_mov_b32_e32 v44, v145
	v_mov_b32_e32 v42, v145
	v_mov_b32_e32 v47, v145
	v_mov_b32_e32 v46, v145
	v_mov_b32_e32 v51, v145
	v_mov_b32_e32 v50, v145
	v_mov_b32_e32 v59, v145
	v_mov_b32_e32 v58, v145
	v_mov_b32_e32 v69, v145
	v_mov_b32_e32 v68, v145
	v_mov_b32_e32 v74, v145
	v_mov_b32_e32 v87, v145
	v_mov_b32_e32 v86, v145
	v_mov_b32_e32 v93, v145
	v_mov_b32_e32 v92, v145
	v_mov_b32_e32 v91, v145
	v_mov_b32_e32 v90, v145
	v_mov_b32_e32 v97, v145
	v_mov_b32_e32 v96, v145
	v_mov_b32_e32 v95, v145
	v_mov_b32_e32 v94, v145
	v_mov_b32_e32 v101, v145
	v_mov_b32_e32 v100, v145
	v_mov_b32_e32 v99, v145
	v_mov_b32_e32 v98, v145
	v_mov_b32_e32 v109, v145
	v_mov_b32_e32 v108, v145
	v_mov_b32_e32 v110, v145
	s_waitcnt lgkmcnt(0)
	s_barrier
	s_cbranch_scc1 .LBB0_501
	s_and_b32 s80, s63, 15
	s_add_i32 s59, s58, 11
	s_add_i32 s58, s58, 12
	s_lshl_b32 s81, s80, 2
	s_cmp_gt_u32 s81, 4
	s_cselect_b32 s81, s81, 4
	s_lshl_b32 s82, s81, 7
	s_add_u32 s82, s68, s82
	s_addc_u32 s83, s69, 0
	s_add_u32 s52, s82, s52
	s_addc_u32 s53, s83, s53
	v_max_i32_e32 v34, 4, v146
	v_lshl_add_u64 v[146:147], s[52:53], 0, v[116:117]
	s_lshl_b64 s[36:37], s[36:37], 26
	s_lshl_b32 s52, s81, 20
	s_or_b32 s36, s36, s52
	s_lshl_b32 s52, s63, 4
	s_and_b32 s52, s52, 0x1f00
	s_or_b32 s36, s36, s52
	v_add_u32_e32 v34, -4, v34
	v_lshl_add_u64 v[148:149], v[132:133], 0, s[36:37]
	s_mul_i32 s36, s46, 0x7c
	s_mulk_i32 s80, 0x1f0
	v_min_u32_e32 v135, 56, v34
	s_sub_i32 s36, s36, s80
	v_mov_b32_e32 v110, 0
	v_add_u32_e32 v180, 7, v135
	v_add_u32_e32 v116, s36, v177
	s_mov_b32 s80, 0
	s_mov_b32 s63, 0
	v_mov_b32_e32 v111, v110
	v_mov_b32_e32 v112, v110
	v_mov_b32_e32 v113, v110
	v_mov_b32_e32 v106, v110
	v_mov_b32_e32 v107, v110
	v_mov_b32_e32 v108, v110
	v_mov_b32_e32 v109, v110
	v_mov_b32_e32 v102, v110
	v_mov_b32_e32 v103, v110
	v_mov_b32_e32 v104, v110
	v_mov_b32_e32 v105, v110
	v_mov_b32_e32 v98, v110
	v_mov_b32_e32 v99, v110
	v_mov_b32_e32 v100, v110
	v_mov_b32_e32 v101, v110
	v_mov_b32_e32 v94, v110
	v_mov_b32_e32 v95, v110
	v_mov_b32_e32 v96, v110
	v_mov_b32_e32 v97, v110
	v_mov_b32_e32 v90, v110
	v_mov_b32_e32 v91, v110
	v_mov_b32_e32 v92, v110
	v_mov_b32_e32 v93, v110
	v_mov_b32_e32 v86, v110
	v_mov_b32_e32 v87, v110
	v_mov_b32_e32 v88, v110
	v_mov_b32_e32 v89, v110
	v_mov_b32_e32 v82, v110
	v_mov_b32_e32 v83, v110
	v_mov_b32_e32 v84, v110
	v_mov_b32_e32 v85, v110
	v_mov_b32_e32 v74, v110
	v_mov_b32_e32 v75, v110
	v_mov_b32_e32 v76, v110
	v_mov_b32_e32 v77, v110
	v_mov_b32_e32 v66, v110
	v_mov_b32_e32 v67, v110
	v_mov_b32_e32 v68, v110
	v_mov_b32_e32 v69, v110
	v_mov_b32_e32 v58, v110
	v_mov_b32_e32 v59, v110
	v_mov_b32_e32 v60, v110
	v_mov_b32_e32 v61, v110
	v_mov_b32_e32 v50, v110
	v_mov_b32_e32 v51, v110
	v_mov_b32_e32 v52, v110
	v_mov_b32_e32 v53, v110
	v_mov_b32_e32 v46, v110
	v_mov_b32_e32 v47, v110
	v_mov_b32_e32 v48, v110
	v_mov_b32_e32 v49, v110
	v_mov_b32_e32 v42, v110
	v_mov_b32_e32 v43, v110
	v_mov_b32_e32 v44, v110
	v_mov_b32_e32 v45, v110
	v_mov_b32_e32 v38, v110
	v_mov_b32_e32 v39, v110
	v_mov_b32_e32 v40, v110
	v_mov_b32_e32 v41, v110
	v_mov_b32_e32 v34, v110
	v_mov_b32_e32 v35, v110
	v_mov_b32_e32 v36, v110
	v_mov_b32_e32 v37, v110
	v_mov_b32_e32 v144, v110
	v_mov_b32_e32 v145, v110
	s_cmp_ge_i32 s63, s59
	s_cselect_b64 s[52:53], -1, 0
	s_and_b64 vcc, exec, s[52:53]
	s_cbranch_vccnz .LBB0_512
	s_branch .LBB0_511
